# counted lgkmcnt(6) for the 4 MFMAs issued before the late opening barrier, full lgkmcnt(0) just before that barrier (on top of v57)
# baseline (speedup 1.0000x reference)
.LBB0_233:
	ds_read_b128 v[130:133], v213
	ds_read_b128 v[134:137], v214
	ds_read_b128 v[138:141], v215
	ds_read_b128 v[142:145], v216
	ds_read_b128 v[146:149], v217
	ds_read_b128 v[150:153], v218
	ds_read_b128 v[154:157], v219
	ds_read_b128 v[158:161], v220
	s_add_i32 s4, s33, 0xffffe080
	s_cmp_eq_u32 s58, 12
	s_cselect_b32 s61, s18, s4
	s_cselect_b32 s60, s19, s57
	s_add_i32 s59, s61, 0x80
	s_mov_b32 s4, s70
	s_mov_b32 m0, s38
	ds_read_b128 v[162:165], v221
	ds_read_b128 v[166:169], v221 offset:2048
	ds_read_b128 v[170:173], v222
	ds_read_b128 v[174:177], v222 offset:2048
	ds_read_b128 v[178:181], v221 offset:4096
	ds_read_b128 v[182:185], v221 offset:6144
	ds_read_b128 v[186:189], v222 offset:4096
	ds_read_b128 v[190:193], v222 offset:6144
	buffer_load_dwordx4 v207, s[4:7], s33 offen lds
	s_mov_b32 m0, s41
	s_nop 0
	buffer_load_dwordx4 v209, s[4:7], s33 offen lds
	s_waitcnt vmcnt(8)
	s_waitcnt lgkmcnt(6)
	s_setprio 1
	v_mfma_f32_16x16x32_bf16 v[114:117], v[130:133], v[162:165], v[114:117]
	v_mfma_f32_16x16x32_bf16 v[110:113], v[138:141], v[162:165], v[110:113]
	v_mfma_f32_16x16x32_bf16 v[106:109], v[130:133], v[166:169], v[106:109]
	v_mfma_f32_16x16x32_bf16 v[102:105], v[138:141], v[166:169], v[102:105]
	s_waitcnt lgkmcnt(0)
	s_barrier
	v_mfma_f32_16x16x32_bf16 v[98:101], v[130:133], v[178:181], v[98:101]
	v_mfma_f32_16x16x32_bf16 v[94:97], v[138:141], v[178:181], v[94:97]
	v_mfma_f32_16x16x32_bf16 v[90:93], v[130:133], v[182:185], v[90:93]
	v_mfma_f32_16x16x32_bf16 v[86:89], v[138:141], v[182:185], v[86:89]
	v_mfma_f32_16x16x32_bf16 v[114:117], v[134:137], v[170:173], v[114:117]
	v_mfma_f32_16x16x32_bf16 v[110:113], v[142:145], v[170:173], v[110:113]
	v_mfma_f32_16x16x32_bf16 v[106:109], v[134:137], v[174:177], v[106:109]
	v_mfma_f32_16x16x32_bf16 v[102:105], v[142:145], v[174:177], v[102:105]
	v_mfma_f32_16x16x32_bf16 v[98:101], v[134:137], v[186:189], v[98:101]
	v_mfma_f32_16x16x32_bf16 v[94:97], v[142:145], v[186:189], v[94:97]
	v_mfma_f32_16x16x32_bf16 v[90:93], v[134:137], v[190:193], v[90:93]
	v_mfma_f32_16x16x32_bf16 v[86:89], v[142:145], v[190:193], v[86:89]
	v_mfma_f32_16x16x32_bf16 v[82:85], v[146:149], v[162:165], v[82:85]
	v_mfma_f32_16x16x32_bf16 v[74:77], v[154:157], v[162:165], v[74:77]
	v_mfma_f32_16x16x32_bf16 v[70:73], v[146:149], v[166:169], v[70:73]
	v_mfma_f32_16x16x32_bf16 v[66:69], v[154:157], v[166:169], v[66:69]
	v_mfma_f32_16x16x32_bf16 v[62:65], v[146:149], v[178:181], v[62:65]
	v_mfma_f32_16x16x32_bf16 v[58:61], v[154:157], v[178:181], v[58:61]
	v_mfma_f32_16x16x32_bf16 v[54:57], v[146:149], v[182:185], v[54:57]
	v_mfma_f32_16x16x32_bf16 v[50:53], v[154:157], v[182:185], v[50:53]
	v_mfma_f32_16x16x32_bf16 v[82:85], v[150:153], v[170:173], v[82:85]
	v_mfma_f32_16x16x32_bf16 v[74:77], v[158:161], v[170:173], v[74:77]
	v_mfma_f32_16x16x32_bf16 v[70:73], v[150:153], v[174:177], v[70:73]
	v_mfma_f32_16x16x32_bf16 v[66:69], v[158:161], v[174:177], v[66:69]
	v_mfma_f32_16x16x32_bf16 v[62:65], v[150:153], v[186:189], v[62:65]
	v_mfma_f32_16x16x32_bf16 v[58:61], v[158:161], v[186:189], v[58:61]
	v_mfma_f32_16x16x32_bf16 v[54:57], v[150:153], v[190:193], v[54:57]
	v_mfma_f32_16x16x32_bf16 v[50:53], v[158:161], v[190:193], v[50:53]
	s_barrier
	s_setprio 0
	s_mov_b32 m0, s21
	ds_read_b128 v[162:165], v221 offset:16384
	ds_read_b128 v[166:169], v221 offset:18432
	ds_read_b128 v[170:173], v222 offset:16384
	ds_read_b128 v[174:177], v222 offset:18432
	ds_read_b128 v[178:181], v221 offset:20480
	ds_read_b128 v[182:185], v221 offset:22528
	ds_read_b128 v[186:189], v222 offset:20480
	ds_read_b128 v[190:193], v222 offset:22528
	buffer_load_dwordx4 v208, s[4:7], s60 offen lds
	s_mov_b32 m0, s22
	s_add_i32 s62, s60, 0x40000
	buffer_load_dwordx4 v210, s[4:7], s60 offen lds
	s_mov_b32 m0, s23
	s_nop 0
	buffer_load_dwordx4 v208, s[4:7], s62 offen lds
	s_mov_b32 m0, s24
	s_nop 0
	buffer_load_dwordx4 v210, s[4:7], s62 offen lds
	s_mov_b32 m0, s20
	s_nop 0
	buffer_load_dwordx4 v207, s[4:7], s61 offen lds
	s_mov_b32 m0, s25
	s_nop 0
	buffer_load_dwordx4 v209, s[4:7], s61 offen lds
	s_waitcnt vmcnt(8)
	s_waitcnt lgkmcnt(0)
	s_setprio 1
	s_barrier
	v_mfma_f32_16x16x32_bf16 v[78:81], v[130:133], v[162:165], v[78:81]
	v_mfma_f32_16x16x32_bf16 v[46:49], v[138:141], v[162:165], v[46:49]
	v_mfma_f32_16x16x32_bf16 v[42:45], v[130:133], v[166:169], v[42:45]
	v_mfma_f32_16x16x32_bf16 v[38:41], v[138:141], v[166:169], v[38:41]
	v_mfma_f32_16x16x32_bf16 v[34:37], v[130:133], v[178:181], v[34:37]
	v_mfma_f32_16x16x32_bf16 v[30:33], v[138:141], v[178:181], v[30:33]
	v_mfma_f32_16x16x32_bf16 v[26:29], v[130:133], v[182:185], v[26:29]
	v_mfma_f32_16x16x32_bf16 v[22:25], v[138:141], v[182:185], v[22:25]
	v_mfma_f32_16x16x32_bf16 v[78:81], v[134:137], v[170:173], v[78:81]
	v_mfma_f32_16x16x32_bf16 v[46:49], v[142:145], v[170:173], v[46:49]
	v_mfma_f32_16x16x32_bf16 v[42:45], v[134:137], v[174:177], v[42:45]
	v_mfma_f32_16x16x32_bf16 v[38:41], v[142:145], v[174:177], v[38:41]
	v_mfma_f32_16x16x32_bf16 v[34:37], v[134:137], v[186:189], v[34:37]
	v_mfma_f32_16x16x32_bf16 v[30:33], v[142:145], v[186:189], v[30:33]
	v_mfma_f32_16x16x32_bf16 v[26:29], v[134:137], v[190:193], v[26:29]
	v_mfma_f32_16x16x32_bf16 v[22:25], v[142:145], v[190:193], v[22:25]
	v_mfma_f32_16x16x32_bf16 v[18:21], v[146:149], v[162:165], v[18:21]
	v_mfma_f32_16x16x32_bf16 v[14:17], v[154:157], v[162:165], v[14:17]
	v_mfma_f32_16x16x32_bf16 v[10:13], v[146:149], v[166:169], v[10:13]
	v_mfma_f32_16x16x32_bf16 v[6:9], v[154:157], v[166:169], v[6:9]
	v_mfma_f32_16x16x32_bf16 v[2:5], v[146:149], v[178:181], v[2:5]
	v_mfma_f32_16x16x32_bf16 v[126:129], v[154:157], v[178:181], v[126:129]
	v_mfma_f32_16x16x32_bf16 v[122:125], v[146:149], v[182:185], v[122:125]
	v_mfma_f32_16x16x32_bf16 v[118:121], v[154:157], v[182:185], v[118:121]
	v_mfma_f32_16x16x32_bf16 v[18:21], v[150:153], v[170:173], v[18:21]
	v_mfma_f32_16x16x32_bf16 v[14:17], v[158:161], v[170:173], v[14:17]
	v_mfma_f32_16x16x32_bf16 v[10:13], v[150:153], v[174:177], v[10:13]
	v_mfma_f32_16x16x32_bf16 v[6:9], v[158:161], v[174:177], v[6:9]
	v_mfma_f32_16x16x32_bf16 v[2:5], v[150:153], v[186:189], v[2:5]
	v_mfma_f32_16x16x32_bf16 v[126:129], v[158:161], v[186:189], v[126:129]
	v_mfma_f32_16x16x32_bf16 v[122:125], v[150:153], v[190:193], v[122:125]
	v_mfma_f32_16x16x32_bf16 v[118:121], v[158:161], v[190:193], v[118:121]
	s_barrier
	s_setprio 0
	ds_read_b128 v[130:133], v194
	ds_read_b128 v[134:137], v224
	ds_read_b128 v[138:141], v225
	ds_read_b128 v[142:145], v228
	ds_read_b128 v[146:149], v229
	ds_read_b128 v[150:153], v230
	ds_read_b128 v[154:157], v231
	ds_read_b128 v[158:161], v233
	s_addk_i32 s61, 0x2000
	s_mov_b32 m0, s26
	ds_read_b128 v[162:165], v221 offset:32768
	ds_read_b128 v[166:169], v221 offset:34816
	ds_read_b128 v[170:173], v222 offset:32768
	ds_read_b128 v[174:177], v222 offset:34816
	ds_read_b128 v[178:181], v221 offset:36864
	ds_read_b128 v[182:185], v221 offset:38912
	ds_read_b128 v[186:189], v222 offset:36864
	ds_read_b128 v[190:193], v222 offset:38912
	buffer_load_dwordx4 v207, s[4:7], s61 offen lds
	s_mov_b32 m0, s27
	s_nop 0
	buffer_load_dwordx4 v209, s[4:7], s61 offen lds
	s_waitcnt vmcnt(8)
	s_waitcnt lgkmcnt(6)
	s_setprio 1
	v_mfma_f32_16x16x32_bf16 v[114:117], v[130:133], v[162:165], v[114:117]
	v_mfma_f32_16x16x32_bf16 v[110:113], v[138:141], v[162:165], v[110:113]
	v_mfma_f32_16x16x32_bf16 v[106:109], v[130:133], v[166:169], v[106:109]
	v_mfma_f32_16x16x32_bf16 v[102:105], v[138:141], v[166:169], v[102:105]
	s_waitcnt lgkmcnt(0)
	s_barrier
	v_mfma_f32_16x16x32_bf16 v[98:101], v[130:133], v[178:181], v[98:101]
	v_mfma_f32_16x16x32_bf16 v[94:97], v[138:141], v[178:181], v[94:97]
	v_mfma_f32_16x16x32_bf16 v[90:93], v[130:133], v[182:185], v[90:93]
	v_mfma_f32_16x16x32_bf16 v[86:89], v[138:141], v[182:185], v[86:89]
	v_mfma_f32_16x16x32_bf16 v[114:117], v[134:137], v[170:173], v[114:117]
	v_mfma_f32_16x16x32_bf16 v[110:113], v[142:145], v[170:173], v[110:113]
	v_mfma_f32_16x16x32_bf16 v[106:109], v[134:137], v[174:177], v[106:109]
	v_mfma_f32_16x16x32_bf16 v[102:105], v[142:145], v[174:177], v[102:105]
	v_mfma_f32_16x16x32_bf16 v[98:101], v[134:137], v[186:189], v[98:101]
	v_mfma_f32_16x16x32_bf16 v[94:97], v[142:145], v[186:189], v[94:97]
	v_mfma_f32_16x16x32_bf16 v[90:93], v[134:137], v[190:193], v[90:93]
	v_mfma_f32_16x16x32_bf16 v[86:89], v[142:145], v[190:193], v[86:89]
	v_mfma_f32_16x16x32_bf16 v[82:85], v[146:149], v[162:165], v[82:85]
	v_mfma_f32_16x16x32_bf16 v[74:77], v[154:157], v[162:165], v[74:77]
	v_mfma_f32_16x16x32_bf16 v[70:73], v[146:149], v[166:169], v[70:73]
	v_mfma_f32_16x16x32_bf16 v[66:69], v[154:157], v[166:169], v[66:69]
	v_mfma_f32_16x16x32_bf16 v[62:65], v[146:149], v[178:181], v[62:65]
	v_mfma_f32_16x16x32_bf16 v[58:61], v[154:157], v[178:181], v[58:61]
	v_mfma_f32_16x16x32_bf16 v[54:57], v[146:149], v[182:185], v[54:57]
	v_mfma_f32_16x16x32_bf16 v[50:53], v[154:157], v[182:185], v[50:53]
	v_mfma_f32_16x16x32_bf16 v[82:85], v[150:153], v[170:173], v[82:85]
	v_mfma_f32_16x16x32_bf16 v[74:77], v[158:161], v[170:173], v[74:77]
	v_mfma_f32_16x16x32_bf16 v[70:73], v[150:153], v[174:177], v[70:73]
	v_mfma_f32_16x16x32_bf16 v[66:69], v[158:161], v[174:177], v[66:69]
	v_mfma_f32_16x16x32_bf16 v[62:65], v[150:153], v[186:189], v[62:65]
	v_mfma_f32_16x16x32_bf16 v[58:61], v[158:161], v[186:189], v[58:61]
	v_mfma_f32_16x16x32_bf16 v[54:57], v[150:153], v[190:193], v[54:57]
	v_mfma_f32_16x16x32_bf16 v[50:53], v[158:161], v[190:193], v[50:53]
	s_barrier
	s_setprio 0
	s_mov_b32 m0, s29
	s_add_i32 s61, s60, 0x80
	ds_read_b128 v[162:165], v221 offset:49152
	ds_read_b128 v[166:169], v221 offset:51200
	ds_read_b128 v[170:173], v222 offset:49152
	ds_read_b128 v[174:177], v222 offset:51200
	ds_read_b128 v[178:181], v221 offset:53248
	ds_read_b128 v[182:185], v221 offset:55296
	ds_read_b128 v[186:189], v222 offset:53248
	ds_read_b128 v[190:193], v222 offset:55296
	buffer_load_dwordx4 v208, s[4:7], s61 offen lds
	s_mov_b32 m0, s30
	s_add_i32 s60, s60, 0x40080
	buffer_load_dwordx4 v210, s[4:7], s61 offen lds
	s_mov_b32 m0, s35
	s_nop 0
	buffer_load_dwordx4 v208, s[4:7], s60 offen lds
	s_mov_b32 m0, s36
	s_nop 0
	buffer_load_dwordx4 v210, s[4:7], s60 offen lds
	s_mov_b32 m0, s31
	s_nop 0
	buffer_load_dwordx4 v207, s[4:7], s59 offen lds
	s_mov_b32 m0, s34
	s_nop 0
	buffer_load_dwordx4 v209, s[4:7], s59 offen lds
	s_waitcnt vmcnt(8)
	s_waitcnt lgkmcnt(0)
	s_setprio 1
	s_barrier
	v_mfma_f32_16x16x32_bf16 v[78:81], v[130:133], v[162:165], v[78:81]
	v_mfma_f32_16x16x32_bf16 v[46:49], v[138:141], v[162:165], v[46:49]
	v_mfma_f32_16x16x32_bf16 v[42:45], v[130:133], v[166:169], v[42:45]
	v_mfma_f32_16x16x32_bf16 v[38:41], v[138:141], v[166:169], v[38:41]
	v_mfma_f32_16x16x32_bf16 v[34:37], v[130:133], v[178:181], v[34:37]
	v_mfma_f32_16x16x32_bf16 v[30:33], v[138:141], v[178:181], v[30:33]
	v_mfma_f32_16x16x32_bf16 v[26:29], v[130:133], v[182:185], v[26:29]
	v_mfma_f32_16x16x32_bf16 v[22:25], v[138:141], v[182:185], v[22:25]
	v_mfma_f32_16x16x32_bf16 v[78:81], v[134:137], v[170:173], v[78:81]
	v_mfma_f32_16x16x32_bf16 v[46:49], v[142:145], v[170:173], v[46:49]
	v_mfma_f32_16x16x32_bf16 v[42:45], v[134:137], v[174:177], v[42:45]
	v_mfma_f32_16x16x32_bf16 v[38:41], v[142:145], v[174:177], v[38:41]
	v_mfma_f32_16x16x32_bf16 v[34:37], v[134:137], v[186:189], v[34:37]
	v_mfma_f32_16x16x32_bf16 v[30:33], v[142:145], v[186:189], v[30:33]
	v_mfma_f32_16x16x32_bf16 v[26:29], v[134:137], v[190:193], v[26:29]
	v_mfma_f32_16x16x32_bf16 v[22:25], v[142:145], v[190:193], v[22:25]
	v_mfma_f32_16x16x32_bf16 v[18:21], v[146:149], v[162:165], v[18:21]
	v_mfma_f32_16x16x32_bf16 v[14:17], v[154:157], v[162:165], v[14:17]
	v_mfma_f32_16x16x32_bf16 v[10:13], v[146:149], v[166:169], v[10:13]
	v_mfma_f32_16x16x32_bf16 v[6:9], v[154:157], v[166:169], v[6:9]
	v_mfma_f32_16x16x32_bf16 v[2:5], v[146:149], v[178:181], v[2:5]
	v_mfma_f32_16x16x32_bf16 v[126:129], v[154:157], v[178:181], v[126:129]
	v_mfma_f32_16x16x32_bf16 v[122:125], v[146:149], v[182:185], v[122:125]
	v_mfma_f32_16x16x32_bf16 v[118:121], v[154:157], v[182:185], v[118:121]
	v_mfma_f32_16x16x32_bf16 v[18:21], v[150:153], v[170:173], v[18:21]
	v_mfma_f32_16x16x32_bf16 v[14:17], v[158:161], v[170:173], v[14:17]
	v_mfma_f32_16x16x32_bf16 v[10:13], v[150:153], v[174:177], v[10:13]
	v_mfma_f32_16x16x32_bf16 v[6:9], v[158:161], v[174:177], v[6:9]
	v_mfma_f32_16x16x32_bf16 v[2:5], v[150:153], v[186:189], v[2:5]
	v_mfma_f32_16x16x32_bf16 v[126:129], v[158:161], v[186:189], v[126:129]
	v_mfma_f32_16x16x32_bf16 v[122:125], v[150:153], v[190:193], v[122:125]
	v_mfma_f32_16x16x32_bf16 v[118:121], v[158:161], v[190:193], v[118:121]
	s_barrier
	s_setprio 0
	s_add_i32 s58, s58, 2
	s_addk_i32 s33, 0x100
	s_addk_i32 s57, 0x100
	s_cmp_gt_u32 s58, 13
	s_cbranch_scc0 .LBB0_233
	s_and_b64 vcc, exec, s[16:17]
	s_cbranch_vccz .LBB0_236
	s_barrier

.LBB0_546:
	ds_read_b128 v[130:133], v211
	ds_read_b128 v[134:137], v212
	ds_read_b128 v[138:141], v213
	ds_read_b128 v[142:145], v214
	ds_read_b128 v[146:149], v215
	ds_read_b128 v[150:153], v216
	ds_read_b128 v[154:157], v217
	ds_read_b128 v[158:161], v218
	s_add_i32 s4, s62, 0x80
	s_cmp_eq_u32 s63, s78
	s_cselect_b32 s84, s64, s4
	s_cselect_b32 s82, s33, s59
	s_cselect_b32 s81, s65, s61
	s_cselect_b32 s80, s56, s60
	s_add_i32 s79, s84, 0x80
	s_add_i32 s83, s60, s62
	s_mov_b32 s4, s70
	s_mov_b32 m0, s43
	ds_read_b128 v[162:165], v219
	ds_read_b128 v[166:169], v219 offset:2048
	ds_read_b128 v[170:173], v220
	ds_read_b128 v[174:177], v220 offset:2048
	ds_read_b128 v[178:181], v219 offset:4096
	ds_read_b128 v[182:185], v219 offset:6144
	ds_read_b128 v[186:189], v220 offset:4096
	ds_read_b128 v[190:193], v220 offset:6144
	buffer_load_dwordx4 v194, s[4:7], s83 offen lds
	s_mov_b32 m0, s44
	s_nop 0
	buffer_load_dwordx4 v222, s[4:7], s83 offen lds
	s_waitcnt vmcnt(8)
	s_waitcnt lgkmcnt(6)
	s_setprio 1
	v_mfma_f32_16x16x32_bf16 v[126:129], v[130:133], v[162:165], v[126:129]
	v_mfma_f32_16x16x32_bf16 v[122:125], v[138:141], v[162:165], v[122:125]
	v_mfma_f32_16x16x32_bf16 v[118:121], v[130:133], v[166:169], v[118:121]
	v_mfma_f32_16x16x32_bf16 v[114:117], v[138:141], v[166:169], v[114:117]
	s_waitcnt lgkmcnt(0)
	s_barrier
	v_mfma_f32_16x16x32_bf16 v[110:113], v[130:133], v[178:181], v[110:113]
	v_mfma_f32_16x16x32_bf16 v[106:109], v[138:141], v[178:181], v[106:109]
	v_mfma_f32_16x16x32_bf16 v[102:105], v[130:133], v[182:185], v[102:105]
	v_mfma_f32_16x16x32_bf16 v[98:101], v[138:141], v[182:185], v[98:101]
	v_mfma_f32_16x16x32_bf16 v[126:129], v[134:137], v[170:173], v[126:129]
	v_mfma_f32_16x16x32_bf16 v[122:125], v[142:145], v[170:173], v[122:125]
	v_mfma_f32_16x16x32_bf16 v[118:121], v[134:137], v[174:177], v[118:121]
	v_mfma_f32_16x16x32_bf16 v[114:117], v[142:145], v[174:177], v[114:117]
	v_mfma_f32_16x16x32_bf16 v[110:113], v[134:137], v[186:189], v[110:113]
	v_mfma_f32_16x16x32_bf16 v[106:109], v[142:145], v[186:189], v[106:109]
	v_mfma_f32_16x16x32_bf16 v[102:105], v[134:137], v[190:193], v[102:105]
	v_mfma_f32_16x16x32_bf16 v[98:101], v[142:145], v[190:193], v[98:101]
	v_mfma_f32_16x16x32_bf16 v[94:97], v[146:149], v[162:165], v[94:97]
	v_mfma_f32_16x16x32_bf16 v[90:93], v[154:157], v[162:165], v[90:93]
	v_mfma_f32_16x16x32_bf16 v[86:89], v[146:149], v[166:169], v[86:89]
	v_mfma_f32_16x16x32_bf16 v[82:85], v[154:157], v[166:169], v[82:85]
	v_mfma_f32_16x16x32_bf16 v[78:81], v[146:149], v[178:181], v[78:81]
	v_mfma_f32_16x16x32_bf16 v[74:77], v[154:157], v[178:181], v[74:77]
	v_mfma_f32_16x16x32_bf16 v[70:73], v[146:149], v[182:185], v[70:73]
	v_mfma_f32_16x16x32_bf16 v[66:69], v[154:157], v[182:185], v[66:69]
	v_mfma_f32_16x16x32_bf16 v[94:97], v[150:153], v[170:173], v[94:97]
	v_mfma_f32_16x16x32_bf16 v[90:93], v[158:161], v[170:173], v[90:93]
	v_mfma_f32_16x16x32_bf16 v[86:89], v[150:153], v[174:177], v[86:89]
	v_mfma_f32_16x16x32_bf16 v[82:85], v[158:161], v[174:177], v[82:85]
	v_mfma_f32_16x16x32_bf16 v[78:81], v[150:153], v[186:189], v[78:81]
	v_mfma_f32_16x16x32_bf16 v[74:77], v[158:161], v[186:189], v[74:77]
	v_mfma_f32_16x16x32_bf16 v[70:73], v[150:153], v[190:193], v[70:73]
	v_mfma_f32_16x16x32_bf16 v[66:69], v[158:161], v[190:193], v[66:69]
	s_barrier
	s_setprio 0
	s_cmp_eq_u32 s82, 0
	s_cselect_b64 s[82:83], -1, 0
	v_cndmask_b32_e64 v233, v200, 0, s[82:83]
	s_mov_b32 m0, s25
	v_sub_u32_e32 v233, v201, v233
	v_cndmask_b32_e64 v234, v203, 0, s[82:83]
	ds_read_b128 v[162:165], v219 offset:16384
	ds_read_b128 v[166:169], v219 offset:18432
	ds_read_b128 v[170:173], v220 offset:16384
	ds_read_b128 v[174:177], v220 offset:18432
	ds_read_b128 v[178:181], v219 offset:20480
	ds_read_b128 v[182:185], v219 offset:22528
	ds_read_b128 v[186:189], v220 offset:20480
	ds_read_b128 v[190:193], v220 offset:22528
	buffer_load_dwordx4 v233, s[4:7], s81 offen lds
	v_sub_u32_e32 v234, v204, v234
	s_mov_b32 m0, s26
	s_add_i32 s85, s81, s80
	buffer_load_dwordx4 v234, s[4:7], s81 offen lds
	s_mov_b32 m0, s27
	v_cndmask_b32_e64 v235, v205, 0, s[82:83]
	buffer_load_dwordx4 v233, s[4:7], s85 offen lds
	s_mov_b32 m0, s28
	v_sub_u32_e32 v235, v1, v235
	buffer_load_dwordx4 v234, s[4:7], s85 offen lds
	s_mov_b32 m0, s24
	v_cndmask_b32_e64 v236, v206, 0, s[82:83]
	buffer_load_dwordx4 v235, s[4:7], s84 offen lds
	v_sub_u32_e32 v236, v202, v236
	s_mov_b32 m0, s29
	s_nop 0
	buffer_load_dwordx4 v236, s[4:7], s84 offen lds
	s_waitcnt vmcnt(8)
	s_waitcnt lgkmcnt(0)
	s_setprio 1
	s_barrier
	v_mfma_f32_16x16x32_bf16 v[62:65], v[130:133], v[162:165], v[62:65]
	v_mfma_f32_16x16x32_bf16 v[58:61], v[138:141], v[162:165], v[58:61]
	v_mfma_f32_16x16x32_bf16 v[54:57], v[130:133], v[166:169], v[54:57]
	v_mfma_f32_16x16x32_bf16 v[50:53], v[138:141], v[166:169], v[50:53]
	v_mfma_f32_16x16x32_bf16 v[46:49], v[130:133], v[178:181], v[46:49]
	v_mfma_f32_16x16x32_bf16 v[42:45], v[138:141], v[178:181], v[42:45]
	v_mfma_f32_16x16x32_bf16 v[38:41], v[130:133], v[182:185], v[38:41]
	v_mfma_f32_16x16x32_bf16 v[34:37], v[138:141], v[182:185], v[34:37]
	v_mfma_f32_16x16x32_bf16 v[62:65], v[134:137], v[170:173], v[62:65]
	v_mfma_f32_16x16x32_bf16 v[58:61], v[142:145], v[170:173], v[58:61]
	v_mfma_f32_16x16x32_bf16 v[54:57], v[134:137], v[174:177], v[54:57]
	v_mfma_f32_16x16x32_bf16 v[50:53], v[142:145], v[174:177], v[50:53]
	v_mfma_f32_16x16x32_bf16 v[46:49], v[134:137], v[186:189], v[46:49]
	v_mfma_f32_16x16x32_bf16 v[42:45], v[142:145], v[186:189], v[42:45]
	v_mfma_f32_16x16x32_bf16 v[38:41], v[134:137], v[190:193], v[38:41]
	v_mfma_f32_16x16x32_bf16 v[34:37], v[142:145], v[190:193], v[34:37]
	v_mfma_f32_16x16x32_bf16 v[30:33], v[146:149], v[162:165], v[30:33]
	v_mfma_f32_16x16x32_bf16 v[26:29], v[154:157], v[162:165], v[26:29]
	v_mfma_f32_16x16x32_bf16 v[22:25], v[146:149], v[166:169], v[22:25]
	v_mfma_f32_16x16x32_bf16 v[18:21], v[154:157], v[166:169], v[18:21]
	v_mfma_f32_16x16x32_bf16 v[14:17], v[146:149], v[178:181], v[14:17]
	v_mfma_f32_16x16x32_bf16 v[10:13], v[154:157], v[178:181], v[10:13]
	v_mfma_f32_16x16x32_bf16 v[6:9], v[146:149], v[182:185], v[6:9]
	v_mfma_f32_16x16x32_bf16 v[2:5], v[154:157], v[182:185], v[2:5]
	v_mfma_f32_16x16x32_bf16 v[30:33], v[150:153], v[170:173], v[30:33]
	v_mfma_f32_16x16x32_bf16 v[26:29], v[158:161], v[170:173], v[26:29]
	v_mfma_f32_16x16x32_bf16 v[22:25], v[150:153], v[174:177], v[22:25]
	v_mfma_f32_16x16x32_bf16 v[18:21], v[158:161], v[174:177], v[18:21]
	v_mfma_f32_16x16x32_bf16 v[14:17], v[150:153], v[186:189], v[14:17]
	v_mfma_f32_16x16x32_bf16 v[10:13], v[158:161], v[186:189], v[10:13]
	v_mfma_f32_16x16x32_bf16 v[6:9], v[150:153], v[190:193], v[6:9]
	v_mfma_f32_16x16x32_bf16 v[2:5], v[158:161], v[190:193], v[2:5]
	s_barrier
	s_setprio 0
	ds_read_b128 v[130:133], v223
	ds_read_b128 v[134:137], v224
	ds_read_b128 v[138:141], v225
	ds_read_b128 v[142:145], v227
	ds_read_b128 v[146:149], v228
	ds_read_b128 v[150:153], v229
	ds_read_b128 v[154:157], v230
	ds_read_b128 v[158:161], v231
	s_add_i32 s84, s84, s80
	s_mov_b32 m0, s30
	ds_read_b128 v[162:165], v219 offset:32768
	ds_read_b128 v[166:169], v219 offset:34816
	ds_read_b128 v[170:173], v220 offset:32768
	ds_read_b128 v[174:177], v220 offset:34816
	ds_read_b128 v[178:181], v219 offset:36864
	ds_read_b128 v[182:185], v219 offset:38912
	ds_read_b128 v[186:189], v220 offset:36864
	ds_read_b128 v[190:193], v220 offset:38912
	buffer_load_dwordx4 v235, s[4:7], s84 offen lds
	s_mov_b32 m0, s31
	s_nop 0
	buffer_load_dwordx4 v236, s[4:7], s84 offen lds
	s_waitcnt vmcnt(8)
	s_waitcnt lgkmcnt(6)
	s_setprio 1
	v_mfma_f32_16x16x32_bf16 v[126:129], v[130:133], v[162:165], v[126:129]
	v_mfma_f32_16x16x32_bf16 v[122:125], v[138:141], v[162:165], v[122:125]
	v_mfma_f32_16x16x32_bf16 v[118:121], v[130:133], v[166:169], v[118:121]
	v_mfma_f32_16x16x32_bf16 v[114:117], v[138:141], v[166:169], v[114:117]
	s_waitcnt lgkmcnt(0)
	s_barrier
	v_mfma_f32_16x16x32_bf16 v[110:113], v[130:133], v[178:181], v[110:113]
	v_mfma_f32_16x16x32_bf16 v[106:109], v[138:141], v[178:181], v[106:109]
	v_mfma_f32_16x16x32_bf16 v[102:105], v[130:133], v[182:185], v[102:105]
	v_mfma_f32_16x16x32_bf16 v[98:101], v[138:141], v[182:185], v[98:101]
	v_mfma_f32_16x16x32_bf16 v[126:129], v[134:137], v[170:173], v[126:129]
	v_mfma_f32_16x16x32_bf16 v[122:125], v[142:145], v[170:173], v[122:125]
	v_mfma_f32_16x16x32_bf16 v[118:121], v[134:137], v[174:177], v[118:121]
	v_mfma_f32_16x16x32_bf16 v[114:117], v[142:145], v[174:177], v[114:117]
	v_mfma_f32_16x16x32_bf16 v[110:113], v[134:137], v[186:189], v[110:113]
	v_mfma_f32_16x16x32_bf16 v[106:109], v[142:145], v[186:189], v[106:109]
	v_mfma_f32_16x16x32_bf16 v[102:105], v[134:137], v[190:193], v[102:105]
	v_mfma_f32_16x16x32_bf16 v[98:101], v[142:145], v[190:193], v[98:101]
	v_mfma_f32_16x16x32_bf16 v[94:97], v[146:149], v[162:165], v[94:97]
	v_mfma_f32_16x16x32_bf16 v[90:93], v[154:157], v[162:165], v[90:93]
	v_mfma_f32_16x16x32_bf16 v[86:89], v[146:149], v[166:169], v[86:89]
	v_mfma_f32_16x16x32_bf16 v[82:85], v[154:157], v[166:169], v[82:85]
	v_mfma_f32_16x16x32_bf16 v[78:81], v[146:149], v[178:181], v[78:81]
	v_mfma_f32_16x16x32_bf16 v[74:77], v[154:157], v[178:181], v[74:77]
	v_mfma_f32_16x16x32_bf16 v[70:73], v[146:149], v[182:185], v[70:73]
	v_mfma_f32_16x16x32_bf16 v[66:69], v[154:157], v[182:185], v[66:69]
	v_mfma_f32_16x16x32_bf16 v[94:97], v[150:153], v[170:173], v[94:97]
	v_mfma_f32_16x16x32_bf16 v[90:93], v[158:161], v[170:173], v[90:93]
	v_mfma_f32_16x16x32_bf16 v[86:89], v[150:153], v[174:177], v[86:89]
	v_mfma_f32_16x16x32_bf16 v[82:85], v[158:161], v[174:177], v[82:85]
	v_mfma_f32_16x16x32_bf16 v[78:81], v[150:153], v[186:189], v[78:81]
	v_mfma_f32_16x16x32_bf16 v[74:77], v[158:161], v[186:189], v[74:77]
	v_mfma_f32_16x16x32_bf16 v[70:73], v[150:153], v[190:193], v[70:73]
	v_mfma_f32_16x16x32_bf16 v[66:69], v[158:161], v[190:193], v[66:69]
	s_barrier
	s_setprio 0
	s_mov_b32 m0, s36
	s_addk_i32 s81, 0x80
	ds_read_b128 v[162:165], v219 offset:49152
	ds_read_b128 v[166:169], v219 offset:51200
	ds_read_b128 v[170:173], v220 offset:49152
	ds_read_b128 v[174:177], v220 offset:51200
	ds_read_b128 v[178:181], v219 offset:53248
	ds_read_b128 v[182:185], v219 offset:55296
	ds_read_b128 v[186:189], v220 offset:53248
	ds_read_b128 v[190:193], v220 offset:55296
	buffer_load_dwordx4 v233, s[4:7], s81 offen lds
	s_mov_b32 m0, s37
	s_nop 0
	buffer_load_dwordx4 v234, s[4:7], s81 offen lds
	s_add_i32 s81, s81, s80
	s_mov_b32 m0, s40
	s_nop 0
	buffer_load_dwordx4 v233, s[4:7], s81 offen lds
	s_mov_b32 m0, s41
	s_nop 0
	buffer_load_dwordx4 v234, s[4:7], s81 offen lds
	s_mov_b32 m0, s38
	s_nop 0
	buffer_load_dwordx4 v235, s[4:7], s79 offen lds
	s_mov_b32 m0, s39
	s_nop 0
	buffer_load_dwordx4 v236, s[4:7], s79 offen lds
	s_waitcnt vmcnt(8)
	s_waitcnt lgkmcnt(0)
	s_setprio 1
	s_barrier
	v_mfma_f32_16x16x32_bf16 v[62:65], v[130:133], v[162:165], v[62:65]
	v_mfma_f32_16x16x32_bf16 v[58:61], v[138:141], v[162:165], v[58:61]
	v_mfma_f32_16x16x32_bf16 v[54:57], v[130:133], v[166:169], v[54:57]
	v_mfma_f32_16x16x32_bf16 v[50:53], v[138:141], v[166:169], v[50:53]
	v_mfma_f32_16x16x32_bf16 v[46:49], v[130:133], v[178:181], v[46:49]
	v_mfma_f32_16x16x32_bf16 v[42:45], v[138:141], v[178:181], v[42:45]
	v_mfma_f32_16x16x32_bf16 v[38:41], v[130:133], v[182:185], v[38:41]
	v_mfma_f32_16x16x32_bf16 v[34:37], v[138:141], v[182:185], v[34:37]
	v_mfma_f32_16x16x32_bf16 v[62:65], v[134:137], v[170:173], v[62:65]
	v_mfma_f32_16x16x32_bf16 v[58:61], v[142:145], v[170:173], v[58:61]
	v_mfma_f32_16x16x32_bf16 v[54:57], v[134:137], v[174:177], v[54:57]
	v_mfma_f32_16x16x32_bf16 v[50:53], v[142:145], v[174:177], v[50:53]
	v_mfma_f32_16x16x32_bf16 v[46:49], v[134:137], v[186:189], v[46:49]
	v_mfma_f32_16x16x32_bf16 v[42:45], v[142:145], v[186:189], v[42:45]
	v_mfma_f32_16x16x32_bf16 v[38:41], v[134:137], v[190:193], v[38:41]
	v_mfma_f32_16x16x32_bf16 v[34:37], v[142:145], v[190:193], v[34:37]
	v_mfma_f32_16x16x32_bf16 v[30:33], v[146:149], v[162:165], v[30:33]
	v_mfma_f32_16x16x32_bf16 v[26:29], v[154:157], v[162:165], v[26:29]
	v_mfma_f32_16x16x32_bf16 v[22:25], v[146:149], v[166:169], v[22:25]
	v_mfma_f32_16x16x32_bf16 v[18:21], v[154:157], v[166:169], v[18:21]
	v_mfma_f32_16x16x32_bf16 v[14:17], v[146:149], v[178:181], v[14:17]
	v_mfma_f32_16x16x32_bf16 v[10:13], v[154:157], v[178:181], v[10:13]
	v_mfma_f32_16x16x32_bf16 v[6:9], v[146:149], v[182:185], v[6:9]
	v_mfma_f32_16x16x32_bf16 v[2:5], v[154:157], v[182:185], v[2:5]
	v_mfma_f32_16x16x32_bf16 v[30:33], v[150:153], v[170:173], v[30:33]
	v_mfma_f32_16x16x32_bf16 v[26:29], v[158:161], v[170:173], v[26:29]
	v_mfma_f32_16x16x32_bf16 v[22:25], v[150:153], v[174:177], v[22:25]
	v_mfma_f32_16x16x32_bf16 v[18:21], v[158:161], v[174:177], v[18:21]
	v_mfma_f32_16x16x32_bf16 v[14:17], v[150:153], v[186:189], v[14:17]
	v_mfma_f32_16x16x32_bf16 v[10:13], v[158:161], v[186:189], v[10:13]
	v_mfma_f32_16x16x32_bf16 v[6:9], v[150:153], v[190:193], v[6:9]
	v_mfma_f32_16x16x32_bf16 v[2:5], v[158:161], v[190:193], v[2:5]
	s_barrier
	s_setprio 0
	s_add_i32 s4, s78, 2
	s_addk_i32 s62, 0x100
	s_addk_i32 s61, 0x100
	s_cmp_ge_u32 s78, s63
	s_mov_b32 s78, s4
	s_cbranch_scc0 .LBB0_546
	s_and_b64 vcc, exec, s[12:13]
	s_cbranch_vccz .LBB0_549
	s_barrier

.LBB0_841:
	ds_read_b128 v[130:133], v240
	ds_read_b128 v[134:137], v241
	ds_read_b128 v[138:141], v242
	ds_read_b128 v[142:145], v243
	ds_read_b128 v[146:149], v244
	ds_read_b128 v[150:153], v245
	ds_read_b128 v[154:157], v246
	ds_read_b128 v[158:161], v247
	s_add_i32 s8, s42, s5
	s_add_i32 s19, s34, s5
	s_add_i32 s18, s8, 0x800
	s_addk_i32 s19, 0x800
	s_cmp_eq_u32 s5, 0
	s_cselect_b32 s20, s0, s18
	s_cselect_b32 s19, s1, s19
	s_add_i32 s18, s20, 0x80
	s_add_i32 s21, s8, 0x40780
	s_mov_b32 s8, s70
	s_mov_b32 m0, s52
	ds_read_b128 v[162:165], v248
	ds_read_b128 v[166:169], v248 offset:2048
	ds_read_b128 v[170:173], v249
	ds_read_b128 v[174:177], v249 offset:2048
	ds_read_b128 v[178:181], v248 offset:4096
	ds_read_b128 v[182:185], v248 offset:6144
	ds_read_b128 v[186:189], v249 offset:4096
	ds_read_b128 v[190:193], v249 offset:6144
	buffer_load_dwordx4 v1, s[8:11], s21 offen lds
	s_mov_b32 m0, s53
	s_nop 0
	buffer_load_dwordx4 v234, s[8:11], s21 offen lds
	s_waitcnt vmcnt(8)
	s_waitcnt lgkmcnt(6)
	s_setprio 1
	v_mfma_f32_16x16x32_bf16 v[74:77], v[130:133], v[162:165], v[74:77]
	v_mfma_f32_16x16x32_bf16 v[70:73], v[138:141], v[162:165], v[70:73]
	v_mfma_f32_16x16x32_bf16 v[66:69], v[130:133], v[166:169], v[66:69]
	v_mfma_f32_16x16x32_bf16 v[82:85], v[138:141], v[166:169], v[82:85]
	s_waitcnt lgkmcnt(0)
	s_barrier
	v_mfma_f32_16x16x32_bf16 v[78:81], v[130:133], v[178:181], v[78:81]
	v_mfma_f32_16x16x32_bf16 v[90:93], v[138:141], v[178:181], v[90:93]
	v_mfma_f32_16x16x32_bf16 v[86:89], v[130:133], v[182:185], v[86:89]
	v_mfma_f32_16x16x32_bf16 v[102:105], v[138:141], v[182:185], v[102:105]
	v_mfma_f32_16x16x32_bf16 v[74:77], v[134:137], v[170:173], v[74:77]
	v_mfma_f32_16x16x32_bf16 v[70:73], v[142:145], v[170:173], v[70:73]
	v_mfma_f32_16x16x32_bf16 v[66:69], v[134:137], v[174:177], v[66:69]
	v_mfma_f32_16x16x32_bf16 v[82:85], v[142:145], v[174:177], v[82:85]
	v_mfma_f32_16x16x32_bf16 v[78:81], v[134:137], v[186:189], v[78:81]
	v_mfma_f32_16x16x32_bf16 v[90:93], v[142:145], v[186:189], v[90:93]
	v_mfma_f32_16x16x32_bf16 v[86:89], v[134:137], v[190:193], v[86:89]
	v_mfma_f32_16x16x32_bf16 v[102:105], v[142:145], v[190:193], v[102:105]
	v_mfma_f32_16x16x32_bf16 v[98:101], v[146:149], v[162:165], v[98:101]
	v_mfma_f32_16x16x32_bf16 v[94:97], v[154:157], v[162:165], v[94:97]
	v_mfma_f32_16x16x32_bf16 v[106:109], v[146:149], v[166:169], v[106:109]
	v_mfma_f32_16x16x32_bf16 v[110:113], v[154:157], v[166:169], v[110:113]
	v_mfma_f32_16x16x32_bf16 v[114:117], v[146:149], v[178:181], v[114:117]
	v_mfma_f32_16x16x32_bf16 v[118:121], v[154:157], v[178:181], v[118:121]
	v_mfma_f32_16x16x32_bf16 v[122:125], v[146:149], v[182:185], v[122:125]
	v_mfma_f32_16x16x32_bf16 v[126:129], v[154:157], v[182:185], v[126:129]
	v_mfma_f32_16x16x32_bf16 v[98:101], v[150:153], v[170:173], v[98:101]
	v_mfma_f32_16x16x32_bf16 v[94:97], v[158:161], v[170:173], v[94:97]
	v_mfma_f32_16x16x32_bf16 v[106:109], v[150:153], v[174:177], v[106:109]
	v_mfma_f32_16x16x32_bf16 v[110:113], v[158:161], v[174:177], v[110:113]
	v_mfma_f32_16x16x32_bf16 v[114:117], v[150:153], v[186:189], v[114:117]
	v_mfma_f32_16x16x32_bf16 v[118:121], v[158:161], v[186:189], v[118:121]
	v_mfma_f32_16x16x32_bf16 v[122:125], v[150:153], v[190:193], v[122:125]
	v_mfma_f32_16x16x32_bf16 v[126:129], v[158:161], v[190:193], v[126:129]
	s_barrier
	s_setprio 0
	s_mov_b32 m0, s29
	ds_read_b128 v[162:165], v248 offset:16384
	ds_read_b128 v[166:169], v248 offset:18432
	ds_read_b128 v[170:173], v249 offset:16384
	ds_read_b128 v[174:177], v249 offset:18432
	ds_read_b128 v[178:181], v248 offset:20480
	ds_read_b128 v[182:185], v248 offset:22528
	ds_read_b128 v[186:189], v249 offset:20480
	ds_read_b128 v[190:193], v249 offset:22528
	buffer_load_dwordx4 v233, s[8:11], s19 offen lds
	s_mov_b32 m0, s30
	s_add_i32 s21, s19, 0x40000
	buffer_load_dwordx4 v235, s[8:11], s19 offen lds
	s_mov_b32 m0, s31
	s_nop 0
	buffer_load_dwordx4 v233, s[8:11], s21 offen lds
	s_mov_b32 m0, s35
	s_nop 0
	buffer_load_dwordx4 v235, s[8:11], s21 offen lds
	s_mov_b32 m0, s28
	s_nop 0
	buffer_load_dwordx4 v1, s[8:11], s20 offen lds
	s_mov_b32 m0, s38
	s_nop 0
	buffer_load_dwordx4 v234, s[8:11], s20 offen lds
	s_waitcnt vmcnt(8)
	s_waitcnt lgkmcnt(0)
	s_setprio 1
	s_barrier
	v_mfma_f32_16x16x32_bf16 v[10:13], v[130:133], v[162:165], v[10:13]
	v_mfma_f32_16x16x32_bf16 v[6:9], v[138:141], v[162:165], v[6:9]
	v_mfma_f32_16x16x32_bf16 v[2:5], v[130:133], v[166:169], v[2:5]
	v_mfma_f32_16x16x32_bf16 v[18:21], v[138:141], v[166:169], v[18:21]
	v_mfma_f32_16x16x32_bf16 v[14:17], v[130:133], v[178:181], v[14:17]
	v_mfma_f32_16x16x32_bf16 v[26:29], v[138:141], v[178:181], v[26:29]
	v_mfma_f32_16x16x32_bf16 v[22:25], v[130:133], v[182:185], v[22:25]
	v_mfma_f32_16x16x32_bf16 v[38:41], v[138:141], v[182:185], v[38:41]
	v_mfma_f32_16x16x32_bf16 v[10:13], v[134:137], v[170:173], v[10:13]
	v_mfma_f32_16x16x32_bf16 v[6:9], v[142:145], v[170:173], v[6:9]
	v_mfma_f32_16x16x32_bf16 v[2:5], v[134:137], v[174:177], v[2:5]
	v_mfma_f32_16x16x32_bf16 v[18:21], v[142:145], v[174:177], v[18:21]
	v_mfma_f32_16x16x32_bf16 v[14:17], v[134:137], v[186:189], v[14:17]
	v_mfma_f32_16x16x32_bf16 v[26:29], v[142:145], v[186:189], v[26:29]
	v_mfma_f32_16x16x32_bf16 v[22:25], v[134:137], v[190:193], v[22:25]
	v_mfma_f32_16x16x32_bf16 v[38:41], v[142:145], v[190:193], v[38:41]
	v_mfma_f32_16x16x32_bf16 v[34:37], v[146:149], v[162:165], v[34:37]
	v_mfma_f32_16x16x32_bf16 v[30:33], v[154:157], v[162:165], v[30:33]
	v_mfma_f32_16x16x32_bf16 v[42:45], v[146:149], v[166:169], v[42:45]
	v_mfma_f32_16x16x32_bf16 v[46:49], v[154:157], v[166:169], v[46:49]
	v_mfma_f32_16x16x32_bf16 v[50:53], v[146:149], v[178:181], v[50:53]
	v_mfma_f32_16x16x32_bf16 v[54:57], v[154:157], v[178:181], v[54:57]
	v_mfma_f32_16x16x32_bf16 v[58:61], v[146:149], v[182:185], v[58:61]
	v_mfma_f32_16x16x32_bf16 v[62:65], v[154:157], v[182:185], v[62:65]
	v_mfma_f32_16x16x32_bf16 v[34:37], v[150:153], v[170:173], v[34:37]
	v_mfma_f32_16x16x32_bf16 v[30:33], v[158:161], v[170:173], v[30:33]
	v_mfma_f32_16x16x32_bf16 v[42:45], v[150:153], v[174:177], v[42:45]
	v_mfma_f32_16x16x32_bf16 v[46:49], v[158:161], v[174:177], v[46:49]
	v_mfma_f32_16x16x32_bf16 v[50:53], v[150:153], v[186:189], v[50:53]
	v_mfma_f32_16x16x32_bf16 v[54:57], v[158:161], v[186:189], v[54:57]
	v_mfma_f32_16x16x32_bf16 v[58:61], v[150:153], v[190:193], v[58:61]
	v_mfma_f32_16x16x32_bf16 v[62:65], v[158:161], v[190:193], v[62:65]
	s_barrier
	s_setprio 0
	ds_read_b128 v[130:133], v194
	ds_read_b128 v[134:137], v195
	ds_read_b128 v[138:141], v196
	ds_read_b128 v[142:145], v197
	ds_read_b128 v[146:149], v198
	ds_read_b128 v[150:153], v199
	ds_read_b128 v[154:157], v200
	ds_read_b128 v[158:161], v201
	s_add_i32 s20, s20, 0x40000
	s_mov_b32 m0, s39
	ds_read_b128 v[162:165], v248 offset:32768
	ds_read_b128 v[166:169], v248 offset:34816
	ds_read_b128 v[170:173], v249 offset:32768
	ds_read_b128 v[174:177], v249 offset:34816
	ds_read_b128 v[178:181], v248 offset:36864
	ds_read_b128 v[182:185], v248 offset:38912
	ds_read_b128 v[186:189], v249 offset:36864
	ds_read_b128 v[190:193], v249 offset:38912
	buffer_load_dwordx4 v1, s[8:11], s20 offen lds
	s_mov_b32 m0, s41
	s_nop 0
	buffer_load_dwordx4 v234, s[8:11], s20 offen lds
	s_waitcnt vmcnt(8)
	s_waitcnt lgkmcnt(6)
	s_setprio 1
	v_mfma_f32_16x16x32_bf16 v[74:77], v[130:133], v[162:165], v[74:77]
	v_mfma_f32_16x16x32_bf16 v[70:73], v[138:141], v[162:165], v[70:73]
	v_mfma_f32_16x16x32_bf16 v[66:69], v[130:133], v[166:169], v[66:69]
	v_mfma_f32_16x16x32_bf16 v[82:85], v[138:141], v[166:169], v[82:85]
	s_waitcnt lgkmcnt(0)
	s_barrier
	v_mfma_f32_16x16x32_bf16 v[78:81], v[130:133], v[178:181], v[78:81]
	v_mfma_f32_16x16x32_bf16 v[90:93], v[138:141], v[178:181], v[90:93]
	v_mfma_f32_16x16x32_bf16 v[86:89], v[130:133], v[182:185], v[86:89]
	v_mfma_f32_16x16x32_bf16 v[102:105], v[138:141], v[182:185], v[102:105]
	v_mfma_f32_16x16x32_bf16 v[74:77], v[134:137], v[170:173], v[74:77]
	v_mfma_f32_16x16x32_bf16 v[70:73], v[142:145], v[170:173], v[70:73]
	v_mfma_f32_16x16x32_bf16 v[66:69], v[134:137], v[174:177], v[66:69]
	v_mfma_f32_16x16x32_bf16 v[82:85], v[142:145], v[174:177], v[82:85]
	v_mfma_f32_16x16x32_bf16 v[78:81], v[134:137], v[186:189], v[78:81]
	v_mfma_f32_16x16x32_bf16 v[90:93], v[142:145], v[186:189], v[90:93]
	v_mfma_f32_16x16x32_bf16 v[86:89], v[134:137], v[190:193], v[86:89]
	v_mfma_f32_16x16x32_bf16 v[102:105], v[142:145], v[190:193], v[102:105]
	v_mfma_f32_16x16x32_bf16 v[98:101], v[146:149], v[162:165], v[98:101]
	v_mfma_f32_16x16x32_bf16 v[94:97], v[154:157], v[162:165], v[94:97]
	v_mfma_f32_16x16x32_bf16 v[106:109], v[146:149], v[166:169], v[106:109]
	v_mfma_f32_16x16x32_bf16 v[110:113], v[154:157], v[166:169], v[110:113]
	v_mfma_f32_16x16x32_bf16 v[114:117], v[146:149], v[178:181], v[114:117]
	v_mfma_f32_16x16x32_bf16 v[118:121], v[154:157], v[178:181], v[118:121]
	v_mfma_f32_16x16x32_bf16 v[122:125], v[146:149], v[182:185], v[122:125]
	v_mfma_f32_16x16x32_bf16 v[126:129], v[154:157], v[182:185], v[126:129]
	v_mfma_f32_16x16x32_bf16 v[98:101], v[150:153], v[170:173], v[98:101]
	v_mfma_f32_16x16x32_bf16 v[94:97], v[158:161], v[170:173], v[94:97]
	v_mfma_f32_16x16x32_bf16 v[106:109], v[150:153], v[174:177], v[106:109]
	v_mfma_f32_16x16x32_bf16 v[110:113], v[158:161], v[174:177], v[110:113]
	v_mfma_f32_16x16x32_bf16 v[114:117], v[150:153], v[186:189], v[114:117]
	v_mfma_f32_16x16x32_bf16 v[118:121], v[158:161], v[186:189], v[118:121]
	v_mfma_f32_16x16x32_bf16 v[122:125], v[150:153], v[190:193], v[122:125]
	v_mfma_f32_16x16x32_bf16 v[126:129], v[158:161], v[190:193], v[126:129]
	s_barrier
	s_setprio 0
	s_mov_b32 m0, s44
	s_add_i32 s20, s19, 0x80
	ds_read_b128 v[162:165], v248 offset:49152
	ds_read_b128 v[166:169], v248 offset:51200
	ds_read_b128 v[170:173], v249 offset:49152
	ds_read_b128 v[174:177], v249 offset:51200
	ds_read_b128 v[178:181], v248 offset:53248
	ds_read_b128 v[182:185], v248 offset:55296
	ds_read_b128 v[186:189], v249 offset:53248
	ds_read_b128 v[190:193], v249 offset:55296
	buffer_load_dwordx4 v233, s[8:11], s20 offen lds
	s_mov_b32 m0, s45
	s_add_i32 s19, s19, 0x40080
	buffer_load_dwordx4 v235, s[8:11], s20 offen lds
	s_mov_b32 m0, s48
	s_nop 0
	buffer_load_dwordx4 v233, s[8:11], s19 offen lds
	s_mov_b32 m0, s49
	s_nop 0
	buffer_load_dwordx4 v235, s[8:11], s19 offen lds
	s_mov_b32 m0, s46
	s_nop 0
	buffer_load_dwordx4 v1, s[8:11], s18 offen lds
	s_mov_b32 m0, s47
	s_nop 0
	buffer_load_dwordx4 v234, s[8:11], s18 offen lds
	s_waitcnt vmcnt(8)
	s_waitcnt lgkmcnt(0)
	s_setprio 1
	s_barrier
	v_mfma_f32_16x16x32_bf16 v[10:13], v[130:133], v[162:165], v[10:13]
	v_mfma_f32_16x16x32_bf16 v[6:9], v[138:141], v[162:165], v[6:9]
	v_mfma_f32_16x16x32_bf16 v[2:5], v[130:133], v[166:169], v[2:5]
	v_mfma_f32_16x16x32_bf16 v[18:21], v[138:141], v[166:169], v[18:21]
	v_mfma_f32_16x16x32_bf16 v[14:17], v[130:133], v[178:181], v[14:17]
	v_mfma_f32_16x16x32_bf16 v[26:29], v[138:141], v[178:181], v[26:29]
	v_mfma_f32_16x16x32_bf16 v[22:25], v[130:133], v[182:185], v[22:25]
	v_mfma_f32_16x16x32_bf16 v[38:41], v[138:141], v[182:185], v[38:41]
	v_mfma_f32_16x16x32_bf16 v[10:13], v[134:137], v[170:173], v[10:13]
	v_mfma_f32_16x16x32_bf16 v[6:9], v[142:145], v[170:173], v[6:9]
	v_mfma_f32_16x16x32_bf16 v[2:5], v[134:137], v[174:177], v[2:5]
	v_mfma_f32_16x16x32_bf16 v[18:21], v[142:145], v[174:177], v[18:21]
	v_mfma_f32_16x16x32_bf16 v[14:17], v[134:137], v[186:189], v[14:17]
	v_mfma_f32_16x16x32_bf16 v[26:29], v[142:145], v[186:189], v[26:29]
	v_mfma_f32_16x16x32_bf16 v[22:25], v[134:137], v[190:193], v[22:25]
	v_mfma_f32_16x16x32_bf16 v[38:41], v[142:145], v[190:193], v[38:41]
	v_mfma_f32_16x16x32_bf16 v[34:37], v[146:149], v[162:165], v[34:37]
	v_mfma_f32_16x16x32_bf16 v[30:33], v[154:157], v[162:165], v[30:33]
	v_mfma_f32_16x16x32_bf16 v[42:45], v[146:149], v[166:169], v[42:45]
	v_mfma_f32_16x16x32_bf16 v[46:49], v[154:157], v[166:169], v[46:49]
	v_mfma_f32_16x16x32_bf16 v[50:53], v[146:149], v[178:181], v[50:53]
	v_mfma_f32_16x16x32_bf16 v[54:57], v[154:157], v[178:181], v[54:57]
	v_mfma_f32_16x16x32_bf16 v[58:61], v[146:149], v[182:185], v[58:61]
	v_mfma_f32_16x16x32_bf16 v[62:65], v[154:157], v[182:185], v[62:65]
	v_mfma_f32_16x16x32_bf16 v[34:37], v[150:153], v[170:173], v[34:37]
	v_mfma_f32_16x16x32_bf16 v[30:33], v[158:161], v[170:173], v[30:33]
	v_mfma_f32_16x16x32_bf16 v[42:45], v[150:153], v[174:177], v[42:45]
	v_mfma_f32_16x16x32_bf16 v[46:49], v[158:161], v[174:177], v[46:49]
	v_mfma_f32_16x16x32_bf16 v[50:53], v[150:153], v[186:189], v[50:53]
	v_mfma_f32_16x16x32_bf16 v[54:57], v[158:161], v[186:189], v[54:57]
	v_mfma_f32_16x16x32_bf16 v[58:61], v[150:153], v[190:193], v[58:61]
	v_mfma_f32_16x16x32_bf16 v[62:65], v[158:161], v[190:193], v[62:65]
	s_barrier
	s_setprio 0
	s_add_i32 s4, s4, 2
	s_addk_i32 s5, 0x100
	s_cmp_gt_u32 s4, 13
	s_cbranch_scc0 .LBB0_841
	s_and_b64 vcc, exec, s[16:17]
	s_cbranch_vccz .LBB0_844
	s_barrier

.LBB0_1122:
	ds_read_b128 v[130:133], v240
	ds_read_b128 v[134:137], v241
	ds_read_b128 v[138:141], v242
	ds_read_b128 v[142:145], v243
	ds_read_b128 v[146:149], v244
	ds_read_b128 v[150:153], v245
	ds_read_b128 v[154:157], v246
	ds_read_b128 v[158:161], v247
	s_add_i32 s8, s31, s53
	s_add_i32 s55, s26, s53
	s_add_i32 s54, s8, 0x800
	s_addk_i32 s55, 0x800
	s_cmp_eq_u32 s53, 0
	s_cselect_b32 s56, s4, s54
	s_cselect_b32 s55, s5, s55
	s_add_i32 s54, s56, 0x80
	s_add_i32 s57, s8, 0x40780
	s_mov_b32 s8, s70
	s_mov_b32 m0, s44
	ds_read_b128 v[162:165], v248
	ds_read_b128 v[166:169], v248 offset:2048
	ds_read_b128 v[170:173], v249
	ds_read_b128 v[174:177], v249 offset:2048
	ds_read_b128 v[178:181], v248 offset:4096
	ds_read_b128 v[182:185], v248 offset:6144
	ds_read_b128 v[186:189], v249 offset:4096
	ds_read_b128 v[190:193], v249 offset:6144
	buffer_load_dwordx4 v1, s[8:11], s57 offen lds
	s_mov_b32 m0, s45
	s_nop 0
	buffer_load_dwordx4 v234, s[8:11], s57 offen lds
	s_waitcnt vmcnt(8)
	s_waitcnt lgkmcnt(6)
	s_setprio 1
	v_mfma_f32_16x16x32_bf16 v[126:129], v[130:133], v[162:165], v[126:129]
	v_mfma_f32_16x16x32_bf16 v[122:125], v[138:141], v[162:165], v[122:125]
	v_mfma_f32_16x16x32_bf16 v[118:121], v[130:133], v[166:169], v[118:121]
	v_mfma_f32_16x16x32_bf16 v[114:117], v[138:141], v[166:169], v[114:117]
	s_waitcnt lgkmcnt(0)
	s_barrier
	v_mfma_f32_16x16x32_bf16 v[110:113], v[130:133], v[178:181], v[110:113]
	v_mfma_f32_16x16x32_bf16 v[106:109], v[138:141], v[178:181], v[106:109]
	v_mfma_f32_16x16x32_bf16 v[102:105], v[130:133], v[182:185], v[102:105]
	v_mfma_f32_16x16x32_bf16 v[98:101], v[138:141], v[182:185], v[98:101]
	v_mfma_f32_16x16x32_bf16 v[126:129], v[134:137], v[170:173], v[126:129]
	v_mfma_f32_16x16x32_bf16 v[122:125], v[142:145], v[170:173], v[122:125]
	v_mfma_f32_16x16x32_bf16 v[118:121], v[134:137], v[174:177], v[118:121]
	v_mfma_f32_16x16x32_bf16 v[114:117], v[142:145], v[174:177], v[114:117]
	v_mfma_f32_16x16x32_bf16 v[110:113], v[134:137], v[186:189], v[110:113]
	v_mfma_f32_16x16x32_bf16 v[106:109], v[142:145], v[186:189], v[106:109]
	v_mfma_f32_16x16x32_bf16 v[102:105], v[134:137], v[190:193], v[102:105]
	v_mfma_f32_16x16x32_bf16 v[98:101], v[142:145], v[190:193], v[98:101]
	v_mfma_f32_16x16x32_bf16 v[94:97], v[146:149], v[162:165], v[94:97]
	v_mfma_f32_16x16x32_bf16 v[90:93], v[154:157], v[162:165], v[90:93]
	v_mfma_f32_16x16x32_bf16 v[86:89], v[146:149], v[166:169], v[86:89]
	v_mfma_f32_16x16x32_bf16 v[82:85], v[154:157], v[166:169], v[82:85]
	v_mfma_f32_16x16x32_bf16 v[78:81], v[146:149], v[178:181], v[78:81]
	v_mfma_f32_16x16x32_bf16 v[74:77], v[154:157], v[178:181], v[74:77]
	v_mfma_f32_16x16x32_bf16 v[70:73], v[146:149], v[182:185], v[70:73]
	v_mfma_f32_16x16x32_bf16 v[66:69], v[154:157], v[182:185], v[66:69]
	v_mfma_f32_16x16x32_bf16 v[94:97], v[150:153], v[170:173], v[94:97]
	v_mfma_f32_16x16x32_bf16 v[90:93], v[158:161], v[170:173], v[90:93]
	v_mfma_f32_16x16x32_bf16 v[86:89], v[150:153], v[174:177], v[86:89]
	v_mfma_f32_16x16x32_bf16 v[82:85], v[158:161], v[174:177], v[82:85]
	v_mfma_f32_16x16x32_bf16 v[78:81], v[150:153], v[186:189], v[78:81]
	v_mfma_f32_16x16x32_bf16 v[74:77], v[158:161], v[186:189], v[74:77]
	v_mfma_f32_16x16x32_bf16 v[70:73], v[150:153], v[190:193], v[70:73]
	v_mfma_f32_16x16x32_bf16 v[66:69], v[158:161], v[190:193], v[66:69]
	s_barrier
	s_setprio 0
	s_mov_b32 m0, s23
	ds_read_b128 v[162:165], v248 offset:16384
	ds_read_b128 v[166:169], v248 offset:18432
	ds_read_b128 v[170:173], v249 offset:16384
	ds_read_b128 v[174:177], v249 offset:18432
	ds_read_b128 v[178:181], v248 offset:20480
	ds_read_b128 v[182:185], v248 offset:22528
	ds_read_b128 v[186:189], v249 offset:20480
	ds_read_b128 v[190:193], v249 offset:22528
	buffer_load_dwordx4 v233, s[8:11], s55 offen lds
	s_mov_b32 m0, s24
	s_add_i32 s57, s55, 0x40000
	buffer_load_dwordx4 v235, s[8:11], s55 offen lds
	s_mov_b32 m0, s25
	s_nop 0
	buffer_load_dwordx4 v233, s[8:11], s57 offen lds
	s_mov_b32 m0, s27
	s_nop 0
	buffer_load_dwordx4 v235, s[8:11], s57 offen lds
	s_mov_b32 m0, s22
	s_nop 0
	buffer_load_dwordx4 v1, s[8:11], s56 offen lds
	s_mov_b32 m0, s28
	s_nop 0
	buffer_load_dwordx4 v234, s[8:11], s56 offen lds
	s_waitcnt vmcnt(8)
	s_waitcnt lgkmcnt(0)
	s_setprio 1
	s_barrier
	v_mfma_f32_16x16x32_bf16 v[62:65], v[130:133], v[162:165], v[62:65]
	v_mfma_f32_16x16x32_bf16 v[58:61], v[138:141], v[162:165], v[58:61]
	v_mfma_f32_16x16x32_bf16 v[54:57], v[130:133], v[166:169], v[54:57]
	v_mfma_f32_16x16x32_bf16 v[50:53], v[138:141], v[166:169], v[50:53]
	v_mfma_f32_16x16x32_bf16 v[46:49], v[130:133], v[178:181], v[46:49]
	v_mfma_f32_16x16x32_bf16 v[42:45], v[138:141], v[178:181], v[42:45]
	v_mfma_f32_16x16x32_bf16 v[38:41], v[130:133], v[182:185], v[38:41]
	v_mfma_f32_16x16x32_bf16 v[34:37], v[138:141], v[182:185], v[34:37]
	v_mfma_f32_16x16x32_bf16 v[62:65], v[134:137], v[170:173], v[62:65]
	v_mfma_f32_16x16x32_bf16 v[58:61], v[142:145], v[170:173], v[58:61]
	v_mfma_f32_16x16x32_bf16 v[54:57], v[134:137], v[174:177], v[54:57]
	v_mfma_f32_16x16x32_bf16 v[50:53], v[142:145], v[174:177], v[50:53]
	v_mfma_f32_16x16x32_bf16 v[46:49], v[134:137], v[186:189], v[46:49]
	v_mfma_f32_16x16x32_bf16 v[42:45], v[142:145], v[186:189], v[42:45]
	v_mfma_f32_16x16x32_bf16 v[38:41], v[134:137], v[190:193], v[38:41]
	v_mfma_f32_16x16x32_bf16 v[34:37], v[142:145], v[190:193], v[34:37]
	v_mfma_f32_16x16x32_bf16 v[30:33], v[146:149], v[162:165], v[30:33]
	v_mfma_f32_16x16x32_bf16 v[26:29], v[154:157], v[162:165], v[26:29]
	v_mfma_f32_16x16x32_bf16 v[22:25], v[146:149], v[166:169], v[22:25]
	v_mfma_f32_16x16x32_bf16 v[18:21], v[154:157], v[166:169], v[18:21]
	v_mfma_f32_16x16x32_bf16 v[14:17], v[146:149], v[178:181], v[14:17]
	v_mfma_f32_16x16x32_bf16 v[10:13], v[154:157], v[178:181], v[10:13]
	v_mfma_f32_16x16x32_bf16 v[6:9], v[146:149], v[182:185], v[6:9]
	v_mfma_f32_16x16x32_bf16 v[2:5], v[154:157], v[182:185], v[2:5]
	v_mfma_f32_16x16x32_bf16 v[30:33], v[150:153], v[170:173], v[30:33]
	v_mfma_f32_16x16x32_bf16 v[26:29], v[158:161], v[170:173], v[26:29]
	v_mfma_f32_16x16x32_bf16 v[22:25], v[150:153], v[174:177], v[22:25]
	v_mfma_f32_16x16x32_bf16 v[18:21], v[158:161], v[174:177], v[18:21]
	v_mfma_f32_16x16x32_bf16 v[14:17], v[150:153], v[186:189], v[14:17]
	v_mfma_f32_16x16x32_bf16 v[10:13], v[158:161], v[186:189], v[10:13]
	v_mfma_f32_16x16x32_bf16 v[6:9], v[150:153], v[190:193], v[6:9]
	v_mfma_f32_16x16x32_bf16 v[2:5], v[158:161], v[190:193], v[2:5]
	s_barrier
	s_setprio 0
	ds_read_b128 v[130:133], v194
	ds_read_b128 v[134:137], v195
	ds_read_b128 v[138:141], v196
	ds_read_b128 v[142:145], v197
	ds_read_b128 v[146:149], v198
	ds_read_b128 v[150:153], v199
	ds_read_b128 v[154:157], v200
	ds_read_b128 v[158:161], v201
	s_add_i32 s56, s56, 0x40000
	s_mov_b32 m0, s29
	ds_read_b128 v[162:165], v248 offset:32768
	ds_read_b128 v[166:169], v248 offset:34816
	ds_read_b128 v[170:173], v249 offset:32768
	ds_read_b128 v[174:177], v249 offset:34816
	ds_read_b128 v[178:181], v248 offset:36864
	ds_read_b128 v[182:185], v248 offset:38912
	ds_read_b128 v[186:189], v249 offset:36864
	ds_read_b128 v[190:193], v249 offset:38912
	buffer_load_dwordx4 v1, s[8:11], s56 offen lds
	s_mov_b32 m0, s30
	s_nop 0
	buffer_load_dwordx4 v234, s[8:11], s56 offen lds
	s_waitcnt vmcnt(8)
	s_waitcnt lgkmcnt(6)
	s_setprio 1
	v_mfma_f32_16x16x32_bf16 v[126:129], v[130:133], v[162:165], v[126:129]
	v_mfma_f32_16x16x32_bf16 v[122:125], v[138:141], v[162:165], v[122:125]
	v_mfma_f32_16x16x32_bf16 v[118:121], v[130:133], v[166:169], v[118:121]
	v_mfma_f32_16x16x32_bf16 v[114:117], v[138:141], v[166:169], v[114:117]
	s_waitcnt lgkmcnt(0)
	s_barrier
	v_mfma_f32_16x16x32_bf16 v[110:113], v[130:133], v[178:181], v[110:113]
	v_mfma_f32_16x16x32_bf16 v[106:109], v[138:141], v[178:181], v[106:109]
	v_mfma_f32_16x16x32_bf16 v[102:105], v[130:133], v[182:185], v[102:105]
	v_mfma_f32_16x16x32_bf16 v[98:101], v[138:141], v[182:185], v[98:101]
	v_mfma_f32_16x16x32_bf16 v[126:129], v[134:137], v[170:173], v[126:129]
	v_mfma_f32_16x16x32_bf16 v[122:125], v[142:145], v[170:173], v[122:125]
	v_mfma_f32_16x16x32_bf16 v[118:121], v[134:137], v[174:177], v[118:121]
	v_mfma_f32_16x16x32_bf16 v[114:117], v[142:145], v[174:177], v[114:117]
	v_mfma_f32_16x16x32_bf16 v[110:113], v[134:137], v[186:189], v[110:113]
	v_mfma_f32_16x16x32_bf16 v[106:109], v[142:145], v[186:189], v[106:109]
	v_mfma_f32_16x16x32_bf16 v[102:105], v[134:137], v[190:193], v[102:105]
	v_mfma_f32_16x16x32_bf16 v[98:101], v[142:145], v[190:193], v[98:101]
	v_mfma_f32_16x16x32_bf16 v[94:97], v[146:149], v[162:165], v[94:97]
	v_mfma_f32_16x16x32_bf16 v[90:93], v[154:157], v[162:165], v[90:93]
	v_mfma_f32_16x16x32_bf16 v[86:89], v[146:149], v[166:169], v[86:89]
	v_mfma_f32_16x16x32_bf16 v[82:85], v[154:157], v[166:169], v[82:85]
	v_mfma_f32_16x16x32_bf16 v[78:81], v[146:149], v[178:181], v[78:81]
	v_mfma_f32_16x16x32_bf16 v[74:77], v[154:157], v[178:181], v[74:77]
	v_mfma_f32_16x16x32_bf16 v[70:73], v[146:149], v[182:185], v[70:73]
	v_mfma_f32_16x16x32_bf16 v[66:69], v[154:157], v[182:185], v[66:69]
	v_mfma_f32_16x16x32_bf16 v[94:97], v[150:153], v[170:173], v[94:97]
	v_mfma_f32_16x16x32_bf16 v[90:93], v[158:161], v[170:173], v[90:93]
	v_mfma_f32_16x16x32_bf16 v[86:89], v[150:153], v[174:177], v[86:89]
	v_mfma_f32_16x16x32_bf16 v[82:85], v[158:161], v[174:177], v[82:85]
	v_mfma_f32_16x16x32_bf16 v[78:81], v[150:153], v[186:189], v[78:81]
	v_mfma_f32_16x16x32_bf16 v[74:77], v[158:161], v[186:189], v[74:77]
	v_mfma_f32_16x16x32_bf16 v[70:73], v[150:153], v[190:193], v[70:73]
	v_mfma_f32_16x16x32_bf16 v[66:69], v[158:161], v[190:193], v[66:69]
	s_barrier
	s_setprio 0
	s_mov_b32 m0, s35
	s_add_i32 s56, s55, 0x80
	ds_read_b128 v[162:165], v248 offset:49152
	ds_read_b128 v[166:169], v248 offset:51200
	ds_read_b128 v[170:173], v249 offset:49152
	ds_read_b128 v[174:177], v249 offset:51200
	ds_read_b128 v[178:181], v248 offset:53248
	ds_read_b128 v[182:185], v248 offset:55296
	ds_read_b128 v[186:189], v249 offset:53248
	ds_read_b128 v[190:193], v249 offset:55296
	buffer_load_dwordx4 v233, s[8:11], s56 offen lds
	s_mov_b32 m0, s36
	s_add_i32 s55, s55, 0x40080
	buffer_load_dwordx4 v235, s[8:11], s56 offen lds
	s_mov_b32 m0, s39
	s_nop 0
	buffer_load_dwordx4 v233, s[8:11], s55 offen lds
	s_mov_b32 m0, s41
	s_nop 0
	buffer_load_dwordx4 v235, s[8:11], s55 offen lds
	s_mov_b32 m0, s37
	s_nop 0
	buffer_load_dwordx4 v1, s[8:11], s54 offen lds
	s_mov_b32 m0, s38
	s_nop 0
	buffer_load_dwordx4 v234, s[8:11], s54 offen lds
	s_waitcnt vmcnt(8)
	s_waitcnt lgkmcnt(0)
	s_setprio 1
	s_barrier
	v_mfma_f32_16x16x32_bf16 v[62:65], v[130:133], v[162:165], v[62:65]
	v_mfma_f32_16x16x32_bf16 v[58:61], v[138:141], v[162:165], v[58:61]
	v_mfma_f32_16x16x32_bf16 v[54:57], v[130:133], v[166:169], v[54:57]
	v_mfma_f32_16x16x32_bf16 v[50:53], v[138:141], v[166:169], v[50:53]
	v_mfma_f32_16x16x32_bf16 v[46:49], v[130:133], v[178:181], v[46:49]
	v_mfma_f32_16x16x32_bf16 v[42:45], v[138:141], v[178:181], v[42:45]
	v_mfma_f32_16x16x32_bf16 v[38:41], v[130:133], v[182:185], v[38:41]
	v_mfma_f32_16x16x32_bf16 v[34:37], v[138:141], v[182:185], v[34:37]
	v_mfma_f32_16x16x32_bf16 v[62:65], v[134:137], v[170:173], v[62:65]
	v_mfma_f32_16x16x32_bf16 v[58:61], v[142:145], v[170:173], v[58:61]
	v_mfma_f32_16x16x32_bf16 v[54:57], v[134:137], v[174:177], v[54:57]
	v_mfma_f32_16x16x32_bf16 v[50:53], v[142:145], v[174:177], v[50:53]
	v_mfma_f32_16x16x32_bf16 v[46:49], v[134:137], v[186:189], v[46:49]
	v_mfma_f32_16x16x32_bf16 v[42:45], v[142:145], v[186:189], v[42:45]
	v_mfma_f32_16x16x32_bf16 v[38:41], v[134:137], v[190:193], v[38:41]
	v_mfma_f32_16x16x32_bf16 v[34:37], v[142:145], v[190:193], v[34:37]
	v_mfma_f32_16x16x32_bf16 v[30:33], v[146:149], v[162:165], v[30:33]
	v_mfma_f32_16x16x32_bf16 v[26:29], v[154:157], v[162:165], v[26:29]
	v_mfma_f32_16x16x32_bf16 v[22:25], v[146:149], v[166:169], v[22:25]
	v_mfma_f32_16x16x32_bf16 v[18:21], v[154:157], v[166:169], v[18:21]
	v_mfma_f32_16x16x32_bf16 v[14:17], v[146:149], v[178:181], v[14:17]
	v_mfma_f32_16x16x32_bf16 v[10:13], v[154:157], v[178:181], v[10:13]
	v_mfma_f32_16x16x32_bf16 v[6:9], v[146:149], v[182:185], v[6:9]
	v_mfma_f32_16x16x32_bf16 v[2:5], v[154:157], v[182:185], v[2:5]
	v_mfma_f32_16x16x32_bf16 v[30:33], v[150:153], v[170:173], v[30:33]
	v_mfma_f32_16x16x32_bf16 v[26:29], v[158:161], v[170:173], v[26:29]
	v_mfma_f32_16x16x32_bf16 v[22:25], v[150:153], v[174:177], v[22:25]
	v_mfma_f32_16x16x32_bf16 v[18:21], v[158:161], v[174:177], v[18:21]
	v_mfma_f32_16x16x32_bf16 v[14:17], v[150:153], v[186:189], v[14:17]
	v_mfma_f32_16x16x32_bf16 v[10:13], v[158:161], v[186:189], v[10:13]
	v_mfma_f32_16x16x32_bf16 v[6:9], v[150:153], v[190:193], v[6:9]
	v_mfma_f32_16x16x32_bf16 v[2:5], v[158:161], v[190:193], v[2:5]
	s_barrier
	s_setprio 0
	s_add_i32 s33, s33, 2
	s_addk_i32 s53, 0x100
	s_cmp_gt_u32 s33, 13
	s_cbranch_scc0 .LBB0_1122
	s_and_b64 vcc, exec, s[16:17]
	s_cbranch_vccz .LBB0_1125
	s_barrier

.LBB0_1251:
	ds_read_b128 v[130:133], v239
	ds_read_b128 v[134:137], v240
	ds_read_b128 v[138:141], v241
	ds_read_b128 v[142:145], v242
	ds_read_b128 v[146:149], v243
	ds_read_b128 v[150:153], v244
	ds_read_b128 v[154:157], v245
	ds_read_b128 v[158:161], v246
	s_add_i32 s8, s51, s5
	s_add_i32 s31, s46, s5
	s_add_i32 s30, s8, 0x2000
	s_addk_i32 s31, 0x2000
	s_cmp_eq_u32 s5, 0
	s_cselect_b32 s33, s0, s30
	s_cselect_b32 s31, s1, s31
	s_add_i32 s30, s33, 0x80
	s_add_i32 s34, s8, 0x101f80
	s_mov_b32 s8, s70
	s_mov_b32 m0, s61
	ds_read_b128 v[162:165], v247
	ds_read_b128 v[166:169], v247 offset:2048
	ds_read_b128 v[170:173], v248
	ds_read_b128 v[174:177], v248 offset:2048
	ds_read_b128 v[178:181], v247 offset:4096
	ds_read_b128 v[182:185], v247 offset:6144
	ds_read_b128 v[186:189], v248 offset:4096
	ds_read_b128 v[190:193], v248 offset:6144
	buffer_load_dwordx4 v230, s[8:11], s34 offen lds
	s_mov_b32 m0, s64
	s_nop 0
	buffer_load_dwordx4 v233, s[8:11], s34 offen lds
	s_waitcnt vmcnt(8)
	s_waitcnt lgkmcnt(6)
	s_setprio 1
	v_mfma_f32_16x16x32_bf16 v[74:77], v[130:133], v[162:165], v[74:77]
	v_mfma_f32_16x16x32_bf16 v[70:73], v[138:141], v[162:165], v[70:73]
	v_mfma_f32_16x16x32_bf16 v[66:69], v[130:133], v[166:169], v[66:69]
	v_mfma_f32_16x16x32_bf16 v[82:85], v[138:141], v[166:169], v[82:85]
	s_waitcnt lgkmcnt(0)
	s_barrier
	v_mfma_f32_16x16x32_bf16 v[78:81], v[130:133], v[178:181], v[78:81]
	v_mfma_f32_16x16x32_bf16 v[90:93], v[138:141], v[178:181], v[90:93]
	v_mfma_f32_16x16x32_bf16 v[86:89], v[130:133], v[182:185], v[86:89]
	v_mfma_f32_16x16x32_bf16 v[102:105], v[138:141], v[182:185], v[102:105]
	v_mfma_f32_16x16x32_bf16 v[74:77], v[134:137], v[170:173], v[74:77]
	v_mfma_f32_16x16x32_bf16 v[70:73], v[142:145], v[170:173], v[70:73]
	v_mfma_f32_16x16x32_bf16 v[66:69], v[134:137], v[174:177], v[66:69]
	v_mfma_f32_16x16x32_bf16 v[82:85], v[142:145], v[174:177], v[82:85]
	v_mfma_f32_16x16x32_bf16 v[78:81], v[134:137], v[186:189], v[78:81]
	v_mfma_f32_16x16x32_bf16 v[90:93], v[142:145], v[186:189], v[90:93]
	v_mfma_f32_16x16x32_bf16 v[86:89], v[134:137], v[190:193], v[86:89]
	v_mfma_f32_16x16x32_bf16 v[102:105], v[142:145], v[190:193], v[102:105]
	v_mfma_f32_16x16x32_bf16 v[98:101], v[146:149], v[162:165], v[98:101]
	v_mfma_f32_16x16x32_bf16 v[94:97], v[154:157], v[162:165], v[94:97]
	v_mfma_f32_16x16x32_bf16 v[106:109], v[146:149], v[166:169], v[106:109]
	v_mfma_f32_16x16x32_bf16 v[110:113], v[154:157], v[166:169], v[110:113]
	v_mfma_f32_16x16x32_bf16 v[114:117], v[146:149], v[178:181], v[114:117]
	v_mfma_f32_16x16x32_bf16 v[118:121], v[154:157], v[178:181], v[118:121]
	v_mfma_f32_16x16x32_bf16 v[122:125], v[146:149], v[182:185], v[122:125]
	v_mfma_f32_16x16x32_bf16 v[126:129], v[154:157], v[182:185], v[126:129]
	v_mfma_f32_16x16x32_bf16 v[98:101], v[150:153], v[170:173], v[98:101]
	v_mfma_f32_16x16x32_bf16 v[94:97], v[158:161], v[170:173], v[94:97]
	v_mfma_f32_16x16x32_bf16 v[106:109], v[150:153], v[174:177], v[106:109]
	v_mfma_f32_16x16x32_bf16 v[110:113], v[158:161], v[174:177], v[110:113]
	v_mfma_f32_16x16x32_bf16 v[114:117], v[150:153], v[186:189], v[114:117]
	v_mfma_f32_16x16x32_bf16 v[118:121], v[158:161], v[186:189], v[118:121]
	v_mfma_f32_16x16x32_bf16 v[122:125], v[150:153], v[190:193], v[122:125]
	v_mfma_f32_16x16x32_bf16 v[126:129], v[158:161], v[190:193], v[126:129]
	s_barrier
	s_setprio 0
	s_mov_b32 m0, s43
	ds_read_b128 v[162:165], v247 offset:16384
	ds_read_b128 v[166:169], v247 offset:18432
	ds_read_b128 v[170:173], v248 offset:16384
	ds_read_b128 v[174:177], v248 offset:18432
	ds_read_b128 v[178:181], v247 offset:20480
	ds_read_b128 v[182:185], v247 offset:22528
	ds_read_b128 v[186:189], v248 offset:20480
	ds_read_b128 v[190:193], v248 offset:22528
	buffer_load_dwordx4 v231, s[8:11], s31 offen lds
	s_mov_b32 m0, s44
	s_add_i32 s34, s31, 0x100000
	buffer_load_dwordx4 v234, s[8:11], s31 offen lds
	s_mov_b32 m0, s45
	s_nop 0
	buffer_load_dwordx4 v231, s[8:11], s34 offen lds
	s_mov_b32 m0, s47
	s_nop 0
	buffer_load_dwordx4 v234, s[8:11], s34 offen lds
	s_mov_b32 m0, s42
	s_nop 0
	buffer_load_dwordx4 v230, s[8:11], s33 offen lds
	s_mov_b32 m0, s48
	s_nop 0
	buffer_load_dwordx4 v233, s[8:11], s33 offen lds
	s_waitcnt vmcnt(8)
	s_waitcnt lgkmcnt(0)
	s_setprio 1
	s_barrier
	v_mfma_f32_16x16x32_bf16 v[10:13], v[130:133], v[162:165], v[10:13]
	v_mfma_f32_16x16x32_bf16 v[6:9], v[138:141], v[162:165], v[6:9]
	v_mfma_f32_16x16x32_bf16 v[0:3], v[130:133], v[166:169], v[2:5]
	v_mfma_f32_16x16x32_bf16 v[18:21], v[138:141], v[166:169], v[18:21]
	v_mfma_f32_16x16x32_bf16 v[14:17], v[130:133], v[178:181], v[14:17]
	v_mfma_f32_16x16x32_bf16 v[26:29], v[138:141], v[178:181], v[26:29]
	v_mfma_f32_16x16x32_bf16 v[22:25], v[130:133], v[182:185], v[22:25]
	v_mfma_f32_16x16x32_bf16 v[38:41], v[138:141], v[182:185], v[38:41]
	v_mfma_f32_16x16x32_bf16 v[10:13], v[134:137], v[170:173], v[10:13]
	v_mfma_f32_16x16x32_bf16 v[6:9], v[142:145], v[170:173], v[6:9]
	v_mfma_f32_16x16x32_bf16 v[0:3], v[134:137], v[174:177], v[0:3]
	v_mfma_f32_16x16x32_bf16 v[18:21], v[142:145], v[174:177], v[18:21]
	v_mfma_f32_16x16x32_bf16 v[14:17], v[134:137], v[186:189], v[14:17]
	v_mfma_f32_16x16x32_bf16 v[26:29], v[142:145], v[186:189], v[26:29]
	v_mfma_f32_16x16x32_bf16 v[22:25], v[134:137], v[190:193], v[22:25]
	v_mfma_f32_16x16x32_bf16 v[38:41], v[142:145], v[190:193], v[38:41]
	v_mfma_f32_16x16x32_bf16 v[34:37], v[146:149], v[162:165], v[34:37]
	v_mfma_f32_16x16x32_bf16 v[30:33], v[154:157], v[162:165], v[30:33]
	v_mfma_f32_16x16x32_bf16 v[42:45], v[146:149], v[166:169], v[42:45]
	v_mfma_f32_16x16x32_bf16 v[46:49], v[154:157], v[166:169], v[46:49]
	v_mfma_f32_16x16x32_bf16 v[50:53], v[146:149], v[178:181], v[50:53]
	v_mfma_f32_16x16x32_bf16 v[54:57], v[154:157], v[178:181], v[54:57]
	v_mfma_f32_16x16x32_bf16 v[58:61], v[146:149], v[182:185], v[58:61]
	v_mfma_f32_16x16x32_bf16 v[62:65], v[154:157], v[182:185], v[62:65]
	v_mfma_f32_16x16x32_bf16 v[34:37], v[150:153], v[170:173], v[34:37]
	v_mfma_f32_16x16x32_bf16 v[30:33], v[158:161], v[170:173], v[30:33]
	v_mfma_f32_16x16x32_bf16 v[42:45], v[150:153], v[174:177], v[42:45]
	v_mfma_f32_16x16x32_bf16 v[46:49], v[158:161], v[174:177], v[46:49]
	v_mfma_f32_16x16x32_bf16 v[50:53], v[150:153], v[186:189], v[50:53]
	v_mfma_f32_16x16x32_bf16 v[54:57], v[158:161], v[186:189], v[54:57]
	v_mfma_f32_16x16x32_bf16 v[58:61], v[150:153], v[190:193], v[58:61]
	v_mfma_f32_16x16x32_bf16 v[62:65], v[158:161], v[190:193], v[62:65]
	s_barrier
	s_setprio 0
	ds_read_b128 v[130:133], v194
	ds_read_b128 v[134:137], v195
	ds_read_b128 v[138:141], v196
	ds_read_b128 v[142:145], v197
	ds_read_b128 v[146:149], v198
	ds_read_b128 v[150:153], v199
	ds_read_b128 v[154:157], v200
	ds_read_b128 v[158:161], v201
	s_add_i32 s33, s33, 0x100000
	s_mov_b32 m0, s49
	ds_read_b128 v[162:165], v247 offset:32768
	ds_read_b128 v[166:169], v247 offset:34816
	ds_read_b128 v[170:173], v248 offset:32768
	ds_read_b128 v[174:177], v248 offset:34816
	ds_read_b128 v[178:181], v247 offset:36864
	ds_read_b128 v[182:185], v247 offset:38912
	ds_read_b128 v[186:189], v248 offset:36864
	ds_read_b128 v[190:193], v248 offset:38912
	buffer_load_dwordx4 v230, s[8:11], s33 offen lds
	s_mov_b32 m0, s50
	s_nop 0
	buffer_load_dwordx4 v233, s[8:11], s33 offen lds
	s_waitcnt vmcnt(8)
	s_waitcnt lgkmcnt(6)
	s_setprio 1
	v_mfma_f32_16x16x32_bf16 v[74:77], v[130:133], v[162:165], v[74:77]
	v_mfma_f32_16x16x32_bf16 v[70:73], v[138:141], v[162:165], v[70:73]
	v_mfma_f32_16x16x32_bf16 v[66:69], v[130:133], v[166:169], v[66:69]
	v_mfma_f32_16x16x32_bf16 v[82:85], v[138:141], v[166:169], v[82:85]
	s_waitcnt lgkmcnt(0)
	s_barrier
	v_mfma_f32_16x16x32_bf16 v[78:81], v[130:133], v[178:181], v[78:81]
	v_mfma_f32_16x16x32_bf16 v[90:93], v[138:141], v[178:181], v[90:93]
	v_mfma_f32_16x16x32_bf16 v[86:89], v[130:133], v[182:185], v[86:89]
	v_mfma_f32_16x16x32_bf16 v[102:105], v[138:141], v[182:185], v[102:105]
	v_mfma_f32_16x16x32_bf16 v[74:77], v[134:137], v[170:173], v[74:77]
	v_mfma_f32_16x16x32_bf16 v[70:73], v[142:145], v[170:173], v[70:73]
	v_mfma_f32_16x16x32_bf16 v[66:69], v[134:137], v[174:177], v[66:69]
	v_mfma_f32_16x16x32_bf16 v[82:85], v[142:145], v[174:177], v[82:85]
	v_mfma_f32_16x16x32_bf16 v[78:81], v[134:137], v[186:189], v[78:81]
	v_mfma_f32_16x16x32_bf16 v[90:93], v[142:145], v[186:189], v[90:93]
	v_mfma_f32_16x16x32_bf16 v[86:89], v[134:137], v[190:193], v[86:89]
	v_mfma_f32_16x16x32_bf16 v[102:105], v[142:145], v[190:193], v[102:105]
	v_mfma_f32_16x16x32_bf16 v[98:101], v[146:149], v[162:165], v[98:101]
	v_mfma_f32_16x16x32_bf16 v[94:97], v[154:157], v[162:165], v[94:97]
	v_mfma_f32_16x16x32_bf16 v[106:109], v[146:149], v[166:169], v[106:109]
	v_mfma_f32_16x16x32_bf16 v[110:113], v[154:157], v[166:169], v[110:113]
	v_mfma_f32_16x16x32_bf16 v[114:117], v[146:149], v[178:181], v[114:117]
	v_mfma_f32_16x16x32_bf16 v[118:121], v[154:157], v[178:181], v[118:121]
	v_mfma_f32_16x16x32_bf16 v[122:125], v[146:149], v[182:185], v[122:125]
	v_mfma_f32_16x16x32_bf16 v[126:129], v[154:157], v[182:185], v[126:129]
	v_mfma_f32_16x16x32_bf16 v[98:101], v[150:153], v[170:173], v[98:101]
	v_mfma_f32_16x16x32_bf16 v[94:97], v[158:161], v[170:173], v[94:97]
	v_mfma_f32_16x16x32_bf16 v[106:109], v[150:153], v[174:177], v[106:109]
	v_mfma_f32_16x16x32_bf16 v[110:113], v[158:161], v[174:177], v[110:113]
	v_mfma_f32_16x16x32_bf16 v[114:117], v[150:153], v[186:189], v[114:117]
	v_mfma_f32_16x16x32_bf16 v[118:121], v[158:161], v[186:189], v[118:121]
	v_mfma_f32_16x16x32_bf16 v[122:125], v[150:153], v[190:193], v[122:125]
	v_mfma_f32_16x16x32_bf16 v[126:129], v[158:161], v[190:193], v[126:129]
	s_barrier
	s_setprio 0
	s_mov_b32 m0, s53
	s_add_i32 s33, s31, 0x80
	ds_read_b128 v[162:165], v247 offset:49152
	ds_read_b128 v[166:169], v247 offset:51200
	ds_read_b128 v[170:173], v248 offset:49152
	ds_read_b128 v[174:177], v248 offset:51200
	ds_read_b128 v[178:181], v247 offset:53248
	ds_read_b128 v[182:185], v247 offset:55296
	ds_read_b128 v[186:189], v248 offset:53248
	ds_read_b128 v[190:193], v248 offset:55296
	buffer_load_dwordx4 v231, s[8:11], s33 offen lds
	s_mov_b32 m0, s54
	s_add_i32 s31, s31, 0x100080
	buffer_load_dwordx4 v234, s[8:11], s33 offen lds
	s_mov_b32 m0, s57
	s_nop 0
	buffer_load_dwordx4 v231, s[8:11], s31 offen lds
	s_mov_b32 m0, s58
	s_nop 0
	buffer_load_dwordx4 v234, s[8:11], s31 offen lds
	s_mov_b32 m0, s55
	s_nop 0
	buffer_load_dwordx4 v230, s[8:11], s30 offen lds
	s_mov_b32 m0, s56
	s_nop 0
	buffer_load_dwordx4 v233, s[8:11], s30 offen lds
	s_waitcnt vmcnt(8)
	s_waitcnt lgkmcnt(0)
	s_setprio 1
	s_barrier
	v_mfma_f32_16x16x32_bf16 v[10:13], v[130:133], v[162:165], v[10:13]
	v_mfma_f32_16x16x32_bf16 v[4:7], v[138:141], v[162:165], v[6:9]
	v_mfma_f32_16x16x32_bf16 v[0:3], v[130:133], v[166:169], v[0:3]
	v_mfma_f32_16x16x32_bf16 v[18:21], v[138:141], v[166:169], v[18:21]
	v_mfma_f32_16x16x32_bf16 v[14:17], v[130:133], v[178:181], v[14:17]
	v_mfma_f32_16x16x32_bf16 v[26:29], v[138:141], v[178:181], v[26:29]
	v_mfma_f32_16x16x32_bf16 v[22:25], v[130:133], v[182:185], v[22:25]
	v_mfma_f32_16x16x32_bf16 v[38:41], v[138:141], v[182:185], v[38:41]
	v_mfma_f32_16x16x32_bf16 v[10:13], v[134:137], v[170:173], v[10:13]
	v_mfma_f32_16x16x32_bf16 v[6:9], v[142:145], v[170:173], v[4:7]
	v_mfma_f32_16x16x32_bf16 v[2:5], v[134:137], v[174:177], v[0:3]
	v_mfma_f32_16x16x32_bf16 v[18:21], v[142:145], v[174:177], v[18:21]
	v_mfma_f32_16x16x32_bf16 v[14:17], v[134:137], v[186:189], v[14:17]
	v_mfma_f32_16x16x32_bf16 v[26:29], v[142:145], v[186:189], v[26:29]
	v_mfma_f32_16x16x32_bf16 v[22:25], v[134:137], v[190:193], v[22:25]
	v_mfma_f32_16x16x32_bf16 v[38:41], v[142:145], v[190:193], v[38:41]
	v_mfma_f32_16x16x32_bf16 v[34:37], v[146:149], v[162:165], v[34:37]
	v_mfma_f32_16x16x32_bf16 v[30:33], v[154:157], v[162:165], v[30:33]
	v_mfma_f32_16x16x32_bf16 v[42:45], v[146:149], v[166:169], v[42:45]
	v_mfma_f32_16x16x32_bf16 v[46:49], v[154:157], v[166:169], v[46:49]
	v_mfma_f32_16x16x32_bf16 v[50:53], v[146:149], v[178:181], v[50:53]
	v_mfma_f32_16x16x32_bf16 v[54:57], v[154:157], v[178:181], v[54:57]
	v_mfma_f32_16x16x32_bf16 v[58:61], v[146:149], v[182:185], v[58:61]
	v_mfma_f32_16x16x32_bf16 v[62:65], v[154:157], v[182:185], v[62:65]
	v_mfma_f32_16x16x32_bf16 v[34:37], v[150:153], v[170:173], v[34:37]
	v_mfma_f32_16x16x32_bf16 v[30:33], v[158:161], v[170:173], v[30:33]
	v_mfma_f32_16x16x32_bf16 v[42:45], v[150:153], v[174:177], v[42:45]
	v_mfma_f32_16x16x32_bf16 v[46:49], v[158:161], v[174:177], v[46:49]
	v_mfma_f32_16x16x32_bf16 v[50:53], v[150:153], v[186:189], v[50:53]
	v_mfma_f32_16x16x32_bf16 v[54:57], v[158:161], v[186:189], v[54:57]
	v_mfma_f32_16x16x32_bf16 v[58:61], v[150:153], v[190:193], v[58:61]
	v_mfma_f32_16x16x32_bf16 v[62:65], v[158:161], v[190:193], v[62:65]
	s_barrier
	s_setprio 0
	s_add_i32 s4, s4, 2
	s_addk_i32 s5, 0x100
	s_cmp_gt_u32 s4, 61
	s_cbranch_scc0 .LBB0_1251
	s_and_b64 vcc, exec, s[18:19]
	s_cbranch_vccz .LBB0_1254
	s_barrier
